# attention queues: 1:1 alternation with the decode unit first in each pair
# speedup vs baseline: 1.0115x; 1.0115x over previous
; __device__ __forceinline__ int fresh_lane() { int l; asm volatile("v_mbcnt_lo_u32_b32 %0, -1, 0\n\tv_mbcnt_hi_u32_b32 %0, -1, %0" : "=v"(l)); return l; }
; #define SEAM(k) do { if (IN(k) && IN((k) + 1)) xcd_barrier(bar, C.wave); } while (0)
; #define PH5 { phase_attention(P, C, (P.pad >> 8) & 3, P.li); }
; #define RUN(k, BODY) do { if (IN(k)) { unsigned char* ws = P.ws; LAUNDER_GPTR(ws); BODY } } while (0)
; __device__ __forceinline__ void phase_attention(const Params& P, const Ctx& C, int parts, int qset) {
;     ...
;     for (int i = 0; i < 8; ++i) { const int x = (x0 + i) & 7;
;         for (;;) {
;             __syncthreads();
;             if (C.wave == 0 && fresh_lane() == 0) *slot = __hip_atomic_fetch_add(qc + 64 * x, 1u, __ATOMIC_RELAXED, __HIP_MEMORY_SCOPE_AGENT);
;             __syncthreads();
;             const unsigned u = *slot;
;             if (u >= 128u) break;
;             const int us = __builtin_amdgcn_readfirstlane((int)u);
; __global__ void __launch_bounds__(NWAVES * 64, 2) fwd_kernel(Params P) {
;     ...
;     RUN(3, PH3); SEAM(3);
;     RUN(4, PH4);
;     RUN(5, PH5); SEAM(5);
.LBB0_1136:
	s_bitcmp1_b32 s101, 1
	s_cbranch_scc1 .Lmy_e7
	s_bitset1_b32 s101, 1
	s_cmpk_lg_i32 s68, 0x100
	s_cbranch_scc1 .Lmy_e7
	s_bitset1_b32 s101, 3
	v_readlane_b32 s99, v254, 10
	s_cmpk_lt_u32 s99, 192
	s_cbranch_scc1 .Lmy_e7
	s_and_b32 s100, s99, 31
	s_mul_i32 s100, s100, 4
	s_add_i32 s100, s100, 0
	s_bitset1_b32 s101, 0
	s_waitcnt vmcnt(0)
	s_barrier
	s_mov_b64 s[2:3], -1
	s_branch .LBB0_1192

; __device__ __forceinline__ void phase_attention(const Params& P, const Ctx& C, int parts, int qset) {
;     ...
;             const int us = __builtin_amdgcn_readfirstlane((int)u);
;             int pq = -1, dq = -1;
;             if (us < 96) { const int k = us / 3, r = us - 3 * k; if (r == 0) pq = 63 - k; else dq = 2 * k + r - 1; } else pq = 127 - us;
;             if (pq >= 0) { if (parts & 1) { if (fixed_ok) attn_prompt_unit<true>(P, C, x, pq); else attn_prompt_unit<false>(P, C, x, pq); } }
.LBB0_1214:
	s_lshr_b32 s2, s5, 1
	s_and_b32 s3, s5, 1
	s_sub_i32 s4, 63, s2
	s_nop 0
	s_nop 0
	s_nop 0
	s_nop 0
	s_nop 0
	s_nop 0
	s_cmp_eq_u32 s3, 1
	s_cselect_b32 s64, s4, -1
	s_cselect_b32 s4, -1, s2
	s_cmp_lt_i32 s64, 0
	s_mov_b64 s[2:3], -1
	s_cbranch_scc0 .LBB0_1212
